# D-type phases: X tile loads issued right after the preceding barrier's release, before the phase dispatch and GEMM prologue, straight into the accumulator registers
# speedup vs baseline: 1.0009x; 1.0009x over previous
; __device__ __forceinline__ void xcd_barrier(const XcdBarrier& b, const bool is_t0) {
;     ...
;     __syncthreads();
; }
;     __device__ __forceinline__ void init(f32x4 (&acc)[2][2][4][2], const pg8::Unit& u, int wr, int wc, int fr, int fq) const {
;         const int row0 = u.pm * 256 + wr * 64 + fr, col0 = u.pn * 256 + wc * 32 + 8 * fq; const float inv = 1.0f / scale;
; #pragma unroll
;         for (int ai = 0; ai < 2; ++ai)
; #pragma unroll
;             for (int m = 0; m < 4; ++m)
; #pragma unroll
;                 for (int bj = 0; bj < 2; ++bj) { const float* xp = X + (size_t)(row0 + ai * 128 + m * 16) * D + col0 + bj * 128; acc[ai][bj][m][0] = *(const f32x4*)xp * inv; acc[ai][bj][m][1] = *(const f32x4*)(xp + 4) * inv; }
;     }
.LBB0_10:
	s_or_b64 exec, exec, s[0:1]
	s_waitcnt lgkmcnt(0)
	s_barrier
	s_and_b32 s100, s57, 7
	s_movk_i32 s101, 0xa2
	s_bitcmp1_b32 s101, s100
	s_cbranch_scc0 .Lxpre_skipC
	v_readlane_b32 s100, v254, 4
	v_readlane_b32 s101, v254, 11
	s_lshl_b32 s100, s100, 20
	s_lshl_b32 s101, s101, 10
	s_add_i32 s100, s100, s101
	s_add_i32 s100, s100, 0x2b00000
	s_add_u32 s100, s6, s100
	s_addc_u32 s101, s7, 0
	v_mbcnt_lo_u32_b32 v240, -1, 0
	v_mbcnt_hi_u32_b32 v240, -1, v240
	v_and_b32_e32 v241, 15, v240
	v_bfe_u32 v240, v240, 4, 2
	v_lshlrev_b32_e32 v241, 12, v241
	v_lshl_or_b32 v241, v240, 5, v241
	s_lshr_b32 vcc_lo, s70, 8
	s_lshl_b32 vcc_lo, vcc_lo, 18
	s_bfe_u32 vcc_hi, s70, 0x20006
	s_lshl_b32 vcc_hi, vcc_hi, 7
	s_or_b32 vcc_lo, vcc_lo, vcc_hi
	v_or_b32_e32 v234, vcc_lo, v241
	v_add_u32_e32 v235, 0x10000, v234
	v_add_u32_e32 v236, 0x20000, v234
	v_add_u32_e32 v237, 0x30000, v234
	v_add_u32_e32 v238, 0x80000, v234
	v_add_u32_e32 v239, 0x90000, v234
	v_add_u32_e32 v240, 0xa0000, v234
	v_add_u32_e32 v241, 0xb0000, v234
	global_load_dwordx4 v[230:233], v234, s[100:101] offset:16
	global_load_dwordx4 v[226:229], v234, s[100:101]
	global_load_dwordx4 v[36:39], v234, s[100:101] offset:528
	global_load_dwordx4 v[32:35], v234, s[100:101] offset:512
	global_load_dwordx4 v[108:111], v235, s[100:101] offset:16
	global_load_dwordx4 v[104:107], v235, s[100:101]
	global_load_dwordx4 v[56:59], v235, s[100:101] offset:528
	global_load_dwordx4 v[52:55], v235, s[100:101] offset:512
	global_load_dwordx4 v[116:119], v236, s[100:101] offset:16
	global_load_dwordx4 v[112:115], v236, s[100:101]
	global_load_dwordx4 v[80:83], v236, s[100:101] offset:528
	global_load_dwordx4 v[72:75], v236, s[100:101] offset:512
	global_load_dwordx4 v[124:127], v237, s[100:101] offset:16
	global_load_dwordx4 v[120:123], v237, s[100:101]
	global_load_dwordx4 v[92:95], v237, s[100:101] offset:528
	global_load_dwordx4 v[88:91], v237, s[100:101] offset:512
	global_load_dwordx4 v[84:87], v238, s[100:101]
	global_load_dwordx4 v[76:79], v238, s[100:101] offset:16
	global_load_dwordx4 v[24:27], v238, s[100:101] offset:528
	global_load_dwordx4 v[28:31], v238, s[100:101] offset:512
	global_load_dwordx4 v[68:71], v239, s[100:101]
	global_load_dwordx4 v[64:67], v239, s[100:101] offset:16
	global_load_dwordx4 v[16:19], v239, s[100:101] offset:528
	global_load_dwordx4 v[20:23], v239, s[100:101] offset:512
	global_load_dwordx4 v[60:63], v240, s[100:101]
	global_load_dwordx4 v[48:51], v240, s[100:101] offset:16
	global_load_dwordx4 v[8:11], v240, s[100:101] offset:528
	global_load_dwordx4 v[12:15], v240, s[100:101] offset:512
	global_load_dwordx4 v[44:47], v241, s[100:101]
	global_load_dwordx4 v[40:43], v241, s[100:101] offset:16
	global_load_dwordx4 v[218:221], v241, s[100:101] offset:528
	global_load_dwordx4 v[222:225], v241, s[100:101] offset:512
.Lxpre_skipC:
.LBB0_11:
	s_add_i32 s33, s33, 1
	s_cmp_ge_i32 s33, s68
	s_cbranch_scc1 .LBB0_651
